# speedup vs baseline: 1.0069x; 1.0006x over previous
; __device__ __forceinline__ void phase0(const Params& p, char* smem) {
;     ...
;         for (int k = 0; k < 128; k += 8) {
;           float wv[8];
; #pragma unroll
;           for (int u = 0; u < 8; ++u) wv[u] = wp[(size_t)(k + u) * 6144];
; #pragma unroll
;           for (int b = 0; b < 33; ++b) {
;             float4 s0 = *(const float4*)(scw + b * 128 + k), s1 = *(const float4*)(scw + b * 128 + k + 4);
;             acc[b] += s0.x * wv[0] + s0.y * wv[1] + s0.z * wv[2] + s0.w * wv[3] + s1.x * wv[4] + s1.y * wv[5] + s1.z * wv[6] + s1.w * wv[7];
;           }
;         }
.LBB0_1949:
	v_add_co_u32_e32 v2, vcc, s63, v56
	global_load_dword v64, v[56:57], off
	s_nop 0
	v_addc_co_u32_e32 v3, vcc, 0, v57, vcc
	global_load_dword v65, v[2:3], off
	v_add_co_u32_e32 v2, vcc, s64, v56
	s_add_i32 s7, s7, 8
	s_nop 0
	v_addc_co_u32_e32 v3, vcc, 0, v57, vcc
	global_load_dword v62, v[2:3], off
	v_add_co_u32_e32 v2, vcc, s65, v56
	s_cmpk_lt_u32 s7, 0x78
	s_nop 0
	v_addc_co_u32_e32 v3, vcc, 0, v57, vcc
	global_load_dword v63, v[2:3], off
	v_add_co_u32_e32 v2, vcc, s66, v56
	v_addc_co_u32_e32 v3, vcc, 0, v57, vcc
	global_load_dword v60, v[2:3], off
	v_add_co_u32_e32 v2, vcc, s67, v56
	v_addc_co_u32_e32 v3, vcc, 0, v57, vcc
	global_load_dword v61, v[2:3], off
	v_add_co_u32_e32 v2, vcc, s68, v56
	v_addc_co_u32_e32 v3, vcc, 0, v57, vcc
	global_load_dword v58, v[2:3], off
	v_add_co_u32_e32 v2, vcc, s69, v56
	s_nop 1
	v_addc_co_u32_e32 v3, vcc, 0, v57, vcc
	global_load_dword v59, v[2:3], off
	s_waitcnt vmcnt(0)
	v_lshl_add_u64 v[56:57], v[56:57], 0, s[40:41]
	ds_read_b128 v[108:111], v80
	ds_read_b128 v[112:115], v80 offset:16
	ds_read_b128 v[116:119], v80 offset:512
	ds_read_b128 v[120:123], v80 offset:528
	ds_read_b128 v[124:127], v80 offset:1024
	ds_read_b128 v[128:131], v80 offset:1040
	s_waitcnt lgkmcnt(4)
	v_fmac_f32_e32 v79, v108, v64
	v_fmac_f32_e32 v79, v109, v65
	v_fmac_f32_e32 v79, v110, v62
	v_fmac_f32_e32 v79, v111, v63
	v_fmac_f32_e32 v79, v112, v60
	v_fmac_f32_e32 v79, v113, v61
	v_fmac_f32_e32 v79, v114, v58
	v_fmac_f32_e32 v79, v115, v59
	ds_read_b128 v[108:111], v80 offset:1536
	ds_read_b128 v[112:115], v80 offset:1552
	s_waitcnt lgkmcnt(4)
	v_fmac_f32_e32 v55, v116, v64
	v_fmac_f32_e32 v55, v117, v65
	v_fmac_f32_e32 v55, v118, v62
	v_fmac_f32_e32 v55, v119, v63
	v_fmac_f32_e32 v55, v120, v60
	v_fmac_f32_e32 v55, v121, v61
	v_fmac_f32_e32 v55, v122, v58
	v_fmac_f32_e32 v55, v123, v59
	ds_read_b128 v[116:119], v80 offset:2048
	ds_read_b128 v[120:123], v80 offset:2064
	s_waitcnt lgkmcnt(4)
	v_fmac_f32_e32 v54, v124, v64
	v_fmac_f32_e32 v54, v125, v65
	v_fmac_f32_e32 v54, v126, v62
	v_fmac_f32_e32 v54, v127, v63
	v_fmac_f32_e32 v54, v128, v60
	v_fmac_f32_e32 v54, v129, v61
	v_fmac_f32_e32 v54, v130, v58
	v_fmac_f32_e32 v54, v131, v59
	ds_read_b128 v[124:127], v80 offset:2560
	ds_read_b128 v[128:131], v80 offset:2576
	s_waitcnt lgkmcnt(4)
	v_fmac_f32_e32 v53, v108, v64
	v_fmac_f32_e32 v53, v109, v65
	v_fmac_f32_e32 v53, v110, v62
	v_fmac_f32_e32 v53, v111, v63
	v_fmac_f32_e32 v53, v112, v60
	v_fmac_f32_e32 v53, v113, v61
	v_fmac_f32_e32 v53, v114, v58
	v_fmac_f32_e32 v53, v115, v59
	ds_read_b128 v[108:111], v80 offset:3072
	ds_read_b128 v[112:115], v80 offset:3088
	s_waitcnt lgkmcnt(4)
	v_fmac_f32_e32 v52, v116, v64
	v_fmac_f32_e32 v52, v117, v65
	v_fmac_f32_e32 v52, v118, v62
	v_fmac_f32_e32 v52, v119, v63
	v_fmac_f32_e32 v52, v120, v60
	v_fmac_f32_e32 v52, v121, v61
	v_fmac_f32_e32 v52, v122, v58
	v_fmac_f32_e32 v52, v123, v59
	ds_read_b128 v[116:119], v80 offset:3584
	ds_read_b128 v[120:123], v80 offset:3600
	s_waitcnt lgkmcnt(4)
	v_fmac_f32_e32 v51, v124, v64
	v_fmac_f32_e32 v51, v125, v65
	v_fmac_f32_e32 v51, v126, v62
	v_fmac_f32_e32 v51, v127, v63
	v_fmac_f32_e32 v51, v128, v60
	v_fmac_f32_e32 v51, v129, v61
	v_fmac_f32_e32 v51, v130, v58
	v_fmac_f32_e32 v51, v131, v59
	ds_read_b128 v[124:127], v80 offset:4096
	ds_read_b128 v[128:131], v80 offset:4112
	s_waitcnt lgkmcnt(4)
	v_fmac_f32_e32 v50, v108, v64
	v_fmac_f32_e32 v50, v109, v65
	v_fmac_f32_e32 v50, v110, v62
	v_fmac_f32_e32 v50, v111, v63
	v_fmac_f32_e32 v50, v112, v60
	v_fmac_f32_e32 v50, v113, v61
	v_fmac_f32_e32 v50, v114, v58
	v_fmac_f32_e32 v50, v115, v59
	ds_read_b128 v[108:111], v80 offset:4608
	ds_read_b128 v[112:115], v80 offset:4624
	s_waitcnt lgkmcnt(4)
	v_fmac_f32_e32 v49, v116, v64
	v_fmac_f32_e32 v49, v117, v65
	v_fmac_f32_e32 v49, v118, v62
	v_fmac_f32_e32 v49, v119, v63
	v_fmac_f32_e32 v49, v120, v60
	v_fmac_f32_e32 v49, v121, v61
	v_fmac_f32_e32 v49, v122, v58
	v_fmac_f32_e32 v49, v123, v59
	ds_read_b128 v[116:119], v80 offset:5120
	ds_read_b128 v[120:123], v80 offset:5136
	s_waitcnt lgkmcnt(4)
	v_fmac_f32_e32 v48, v124, v64
	v_fmac_f32_e32 v48, v125, v65
	v_fmac_f32_e32 v48, v126, v62
	v_fmac_f32_e32 v48, v127, v63
	v_fmac_f32_e32 v48, v128, v60
	v_fmac_f32_e32 v48, v129, v61
	v_fmac_f32_e32 v48, v130, v58
	v_fmac_f32_e32 v48, v131, v59
	ds_read_b128 v[124:127], v80 offset:5632
	ds_read_b128 v[128:131], v80 offset:5648
	s_waitcnt lgkmcnt(4)
	v_fmac_f32_e32 v47, v108, v64
	v_fmac_f32_e32 v47, v109, v65
	v_fmac_f32_e32 v47, v110, v62
	v_fmac_f32_e32 v47, v111, v63
	v_fmac_f32_e32 v47, v112, v60
	v_fmac_f32_e32 v47, v113, v61
	v_fmac_f32_e32 v47, v114, v58
	v_fmac_f32_e32 v47, v115, v59
	ds_read_b128 v[108:111], v80 offset:6144
	ds_read_b128 v[112:115], v80 offset:6160
	s_waitcnt lgkmcnt(4)
	v_fmac_f32_e32 v46, v116, v64
	v_fmac_f32_e32 v46, v117, v65
	v_fmac_f32_e32 v46, v118, v62
	v_fmac_f32_e32 v46, v119, v63
	v_fmac_f32_e32 v46, v120, v60
	v_fmac_f32_e32 v46, v121, v61
	v_fmac_f32_e32 v46, v122, v58
	v_fmac_f32_e32 v46, v123, v59
	ds_read_b128 v[116:119], v80 offset:6656
	ds_read_b128 v[120:123], v80 offset:6672
	s_waitcnt lgkmcnt(4)
	v_fmac_f32_e32 v45, v124, v64
	v_fmac_f32_e32 v45, v125, v65
	v_fmac_f32_e32 v45, v126, v62
	v_fmac_f32_e32 v45, v127, v63
	v_fmac_f32_e32 v45, v128, v60
	v_fmac_f32_e32 v45, v129, v61
	v_fmac_f32_e32 v45, v130, v58
	v_fmac_f32_e32 v45, v131, v59
	ds_read_b128 v[124:127], v80 offset:7168
	ds_read_b128 v[128:131], v80 offset:7184
	s_waitcnt lgkmcnt(4)
; __device__ __forceinline__ void phase0(const Params& p, char* smem) {
;     ...
;         for (int k = 0; k < 128; k += 8) {
;           float wv[8];
; #pragma unroll
;           for (int u = 0; u < 8; ++u) wv[u] = wp[(size_t)(k + u) * 6144];
; #pragma unroll
;           for (int b = 0; b < 33; ++b) {
;             float4 s0 = *(const float4*)(scw + b * 128 + k), s1 = *(const float4*)(scw + b * 128 + k + 4);
;             acc[b] += s0.x * wv[0] + s0.y * wv[1] + s0.z * wv[2] + s0.w * wv[3] + s1.x * wv[4] + s1.y * wv[5] + s1.z * wv[6] + s1.w * wv[7];
;           }
;         }
	v_fmac_f32_e32 v44, v108, v64
	v_fmac_f32_e32 v44, v109, v65
	v_fmac_f32_e32 v44, v110, v62
	v_fmac_f32_e32 v44, v111, v63
	v_fmac_f32_e32 v44, v112, v60
	v_fmac_f32_e32 v44, v113, v61
	v_fmac_f32_e32 v44, v114, v58
	v_fmac_f32_e32 v44, v115, v59
	ds_read_b128 v[108:111], v80 offset:7680
	ds_read_b128 v[112:115], v80 offset:7696
	s_waitcnt lgkmcnt(4)
	v_fmac_f32_e32 v43, v116, v64
	v_fmac_f32_e32 v43, v117, v65
	v_fmac_f32_e32 v43, v118, v62
	v_fmac_f32_e32 v43, v119, v63
	v_fmac_f32_e32 v43, v120, v60
	v_fmac_f32_e32 v43, v121, v61
	v_fmac_f32_e32 v43, v122, v58
	v_fmac_f32_e32 v43, v123, v59
	ds_read_b128 v[116:119], v80 offset:8192
	ds_read_b128 v[120:123], v80 offset:8208
	s_waitcnt lgkmcnt(4)
	v_fmac_f32_e32 v42, v124, v64
	v_fmac_f32_e32 v42, v125, v65
	v_fmac_f32_e32 v42, v126, v62
	v_fmac_f32_e32 v42, v127, v63
	v_fmac_f32_e32 v42, v128, v60
	v_fmac_f32_e32 v42, v129, v61
	v_fmac_f32_e32 v42, v130, v58
	v_fmac_f32_e32 v42, v131, v59
	ds_read_b128 v[124:127], v80 offset:8704
	ds_read_b128 v[128:131], v80 offset:8720
	s_waitcnt lgkmcnt(4)
	v_fmac_f32_e32 v41, v108, v64
	v_fmac_f32_e32 v41, v109, v65
	v_fmac_f32_e32 v41, v110, v62
	v_fmac_f32_e32 v41, v111, v63
	v_fmac_f32_e32 v41, v112, v60
	v_fmac_f32_e32 v41, v113, v61
	v_fmac_f32_e32 v41, v114, v58
	v_fmac_f32_e32 v41, v115, v59
	ds_read_b128 v[108:111], v80 offset:9216
	ds_read_b128 v[112:115], v80 offset:9232
	s_waitcnt lgkmcnt(4)
	v_fmac_f32_e32 v40, v116, v64
	v_fmac_f32_e32 v40, v117, v65
	v_fmac_f32_e32 v40, v118, v62
	v_fmac_f32_e32 v40, v119, v63
	v_fmac_f32_e32 v40, v120, v60
	v_fmac_f32_e32 v40, v121, v61
	v_fmac_f32_e32 v40, v122, v58
	v_fmac_f32_e32 v40, v123, v59
	ds_read_b128 v[116:119], v80 offset:9728
	ds_read_b128 v[120:123], v80 offset:9744
	s_waitcnt lgkmcnt(4)
	v_fmac_f32_e32 v39, v124, v64
	v_fmac_f32_e32 v39, v125, v65
	v_fmac_f32_e32 v39, v126, v62
	v_fmac_f32_e32 v39, v127, v63
	v_fmac_f32_e32 v39, v128, v60
	v_fmac_f32_e32 v39, v129, v61
	v_fmac_f32_e32 v39, v130, v58
	v_fmac_f32_e32 v39, v131, v59
	ds_read_b128 v[124:127], v80 offset:10240
	ds_read_b128 v[128:131], v80 offset:10256
	s_waitcnt lgkmcnt(4)
	v_fmac_f32_e32 v38, v108, v64
	v_fmac_f32_e32 v38, v109, v65
	v_fmac_f32_e32 v38, v110, v62
	v_fmac_f32_e32 v38, v111, v63
	v_fmac_f32_e32 v38, v112, v60
	v_fmac_f32_e32 v38, v113, v61
	v_fmac_f32_e32 v38, v114, v58
	v_fmac_f32_e32 v38, v115, v59
	ds_read_b128 v[108:111], v80 offset:10752
	ds_read_b128 v[112:115], v80 offset:10768
	s_waitcnt lgkmcnt(4)
	v_fmac_f32_e32 v37, v116, v64
	v_fmac_f32_e32 v37, v117, v65
	v_fmac_f32_e32 v37, v118, v62
	v_fmac_f32_e32 v37, v119, v63
	v_fmac_f32_e32 v37, v120, v60
	v_fmac_f32_e32 v37, v121, v61
	v_fmac_f32_e32 v37, v122, v58
	v_fmac_f32_e32 v37, v123, v59
	ds_read_b128 v[116:119], v80 offset:11264
	ds_read_b128 v[120:123], v80 offset:11280
	s_waitcnt lgkmcnt(4)
	v_fmac_f32_e32 v36, v124, v64
	v_fmac_f32_e32 v36, v125, v65
	v_fmac_f32_e32 v36, v126, v62
	v_fmac_f32_e32 v36, v127, v63
	v_fmac_f32_e32 v36, v128, v60
	v_fmac_f32_e32 v36, v129, v61
	v_fmac_f32_e32 v36, v130, v58
	v_fmac_f32_e32 v36, v131, v59
	ds_read_b128 v[124:127], v80 offset:11776
	ds_read_b128 v[128:131], v80 offset:11792
	s_waitcnt lgkmcnt(4)
	v_fmac_f32_e32 v33, v108, v64
	v_fmac_f32_e32 v33, v109, v65
	v_fmac_f32_e32 v33, v110, v62
	v_fmac_f32_e32 v33, v111, v63
	v_fmac_f32_e32 v33, v112, v60
	v_fmac_f32_e32 v33, v113, v61
	v_fmac_f32_e32 v33, v114, v58
	v_fmac_f32_e32 v33, v115, v59
	ds_read_b128 v[108:111], v80 offset:12288
	ds_read_b128 v[112:115], v80 offset:12304
	s_waitcnt lgkmcnt(4)
	v_fmac_f32_e32 v32, v116, v64
	v_fmac_f32_e32 v32, v117, v65
	v_fmac_f32_e32 v32, v118, v62
	v_fmac_f32_e32 v32, v119, v63
	v_fmac_f32_e32 v32, v120, v60
	v_fmac_f32_e32 v32, v121, v61
	v_fmac_f32_e32 v32, v122, v58
	v_fmac_f32_e32 v32, v123, v59
	ds_read_b128 v[116:119], v80 offset:12800
	ds_read_b128 v[120:123], v80 offset:12816
	s_waitcnt lgkmcnt(4)
	v_fmac_f32_e32 v31, v124, v64
	v_fmac_f32_e32 v31, v125, v65
	v_fmac_f32_e32 v31, v126, v62
	v_fmac_f32_e32 v31, v127, v63
	v_fmac_f32_e32 v31, v128, v60
	v_fmac_f32_e32 v31, v129, v61
	v_fmac_f32_e32 v31, v130, v58
	v_fmac_f32_e32 v31, v131, v59
	ds_read_b128 v[124:127], v80 offset:13312
	ds_read_b128 v[128:131], v80 offset:13328
	s_waitcnt lgkmcnt(4)
; __device__ __forceinline__ void phase0(const Params& p, char* smem) {
;     ...
;         for (int k = 0; k < 128; k += 8) {
;           float wv[8];
; #pragma unroll
;           for (int u = 0; u < 8; ++u) wv[u] = wp[(size_t)(k + u) * 6144];
; #pragma unroll
;           for (int b = 0; b < 33; ++b) {
;             float4 s0 = *(const float4*)(scw + b * 128 + k), s1 = *(const float4*)(scw + b * 128 + k + 4);
;             acc[b] += s0.x * wv[0] + s0.y * wv[1] + s0.z * wv[2] + s0.w * wv[3] + s1.x * wv[4] + s1.y * wv[5] + s1.z * wv[6] + s1.w * wv[7];
;           }
;         }
;       }
;       __syncthreads();
;       float* red = (float*)hsm;
; #pragma unroll
;       for (int b = 0; b < 33; ++b) red[(w * 33 + b) * 64 + lane] = acc[b];
;       __syncthreads();
	v_fmac_f32_e32 v30, v108, v64
	v_fmac_f32_e32 v30, v109, v65
	v_fmac_f32_e32 v30, v110, v62
	v_fmac_f32_e32 v30, v111, v63
	v_fmac_f32_e32 v30, v112, v60
	v_fmac_f32_e32 v30, v113, v61
	v_fmac_f32_e32 v30, v114, v58
	v_fmac_f32_e32 v30, v115, v59
	ds_read_b128 v[108:111], v80 offset:13824
	ds_read_b128 v[112:115], v80 offset:13840
	s_waitcnt lgkmcnt(4)
	v_fmac_f32_e32 v29, v116, v64
	v_fmac_f32_e32 v29, v117, v65
	v_fmac_f32_e32 v29, v118, v62
	v_fmac_f32_e32 v29, v119, v63
	v_fmac_f32_e32 v29, v120, v60
	v_fmac_f32_e32 v29, v121, v61
	v_fmac_f32_e32 v29, v122, v58
	v_fmac_f32_e32 v29, v123, v59
	ds_read_b128 v[116:119], v80 offset:14336
	ds_read_b128 v[120:123], v80 offset:14352
	s_waitcnt lgkmcnt(4)
	v_fmac_f32_e32 v28, v124, v64
	v_fmac_f32_e32 v28, v125, v65
	v_fmac_f32_e32 v28, v126, v62
	v_fmac_f32_e32 v28, v127, v63
	v_fmac_f32_e32 v28, v128, v60
	v_fmac_f32_e32 v28, v129, v61
	v_fmac_f32_e32 v28, v130, v58
	v_fmac_f32_e32 v28, v131, v59
	ds_read_b128 v[124:127], v80 offset:14848
	ds_read_b128 v[128:131], v80 offset:14864
	s_waitcnt lgkmcnt(4)
	v_fmac_f32_e32 v27, v108, v64
	v_fmac_f32_e32 v27, v109, v65
	v_fmac_f32_e32 v27, v110, v62
	v_fmac_f32_e32 v27, v111, v63
	v_fmac_f32_e32 v27, v112, v60
	v_fmac_f32_e32 v27, v113, v61
	v_fmac_f32_e32 v27, v114, v58
	v_fmac_f32_e32 v27, v115, v59
	ds_read_b128 v[108:111], v80 offset:15360
	ds_read_b128 v[112:115], v80 offset:15376
	s_waitcnt lgkmcnt(4)
	v_fmac_f32_e32 v26, v116, v64
	v_fmac_f32_e32 v26, v117, v65
	v_fmac_f32_e32 v26, v118, v62
	v_fmac_f32_e32 v26, v119, v63
	v_fmac_f32_e32 v26, v120, v60
	v_fmac_f32_e32 v26, v121, v61
	v_fmac_f32_e32 v26, v122, v58
	v_fmac_f32_e32 v26, v123, v59
	ds_read_b128 v[116:119], v80 offset:15872
	ds_read_b128 v[120:123], v80 offset:15888
	s_waitcnt lgkmcnt(4)
	v_fmac_f32_e32 v25, v124, v64
	v_fmac_f32_e32 v25, v125, v65
	v_fmac_f32_e32 v25, v126, v62
	v_fmac_f32_e32 v25, v127, v63
	v_fmac_f32_e32 v25, v128, v60
	v_fmac_f32_e32 v25, v129, v61
	v_fmac_f32_e32 v25, v130, v58
	v_fmac_f32_e32 v25, v131, v59
	ds_read_b128 v[124:127], v80 offset:16384
	ds_read_b128 v[128:131], v80 offset:16400
	s_waitcnt lgkmcnt(4)
	v_fmac_f32_e32 v24, v108, v64
	v_fmac_f32_e32 v24, v109, v65
	v_fmac_f32_e32 v24, v110, v62
	v_fmac_f32_e32 v24, v111, v63
	v_fmac_f32_e32 v24, v112, v60
	v_fmac_f32_e32 v24, v113, v61
	v_fmac_f32_e32 v24, v114, v58
	v_fmac_f32_e32 v24, v115, v59
	s_waitcnt lgkmcnt(2)
	v_fmac_f32_e32 v23, v116, v64
	v_fmac_f32_e32 v23, v117, v65
	v_fmac_f32_e32 v23, v118, v62
	v_fmac_f32_e32 v23, v119, v63
	v_fmac_f32_e32 v23, v120, v60
	v_fmac_f32_e32 v23, v121, v61
	v_fmac_f32_e32 v23, v122, v58
	v_fmac_f32_e32 v23, v123, v59
	s_waitcnt lgkmcnt(0)
	v_fmac_f32_e32 v22, v124, v64
	v_fmac_f32_e32 v22, v125, v65
	v_fmac_f32_e32 v22, v126, v62
	v_fmac_f32_e32 v22, v127, v63
	v_fmac_f32_e32 v22, v128, v60
	v_fmac_f32_e32 v22, v129, v61
	v_fmac_f32_e32 v22, v130, v58
	v_fmac_f32_e32 v22, v131, v59
	v_add_u32_e32 v80, 32, v80
	s_cbranch_scc1 .LBB0_1949
	s_movk_i32 s7, 0x80
	s_mov_b64 s[18:19], 0
	s_and_b64 vcc, exec, s[16:17]
	s_cbranch_vccz .LBB0_1942
	s_mul_i32 s7, s8, 0x1800
	s_add_i32 s10, s7, s6
	s_mul_i32 s8, s8, 33
	s_ashr_i32 s7, s6, 31
	s_ashr_i32 s9, s8, 31
	s_lshl_b64 s[6:7], s[6:7], 2
	v_lshl_add_u64 v[4:5], v[20:21], 0, s[8:9]
	v_mov_b64_e32 v[6:7], s[6:7]
	v_or_b32_e32 v2, s10, v16
	v_mad_u64_u32 v[6:7], s[6:7], v4, s63, v[6:7]
	v_ashrrev_i32_e32 v3, 31, v2
	v_mad_i32_i24 v7, v5, s63, v7
	v_lshl_add_u64 v[2:3], v[2:3], 2, s[20:21]
	v_lshl_add_u64 v[4:5], v[18:19], 0, v[6:7]
	s_mov_b64 s[6:7], 0
	v_mov_b32_e32 v6, v77
	v_mov_b32_e32 v7, v76
	v_mov_b32_e32 v8, v75
	s_barrier
	ds_write2st64_b32 v78, v79, v55 offset1:1
	ds_write2st64_b32 v78, v54, v53 offset0:2 offset1:3
	ds_write2st64_b32 v78, v52, v51 offset0:4 offset1:5
	ds_write2st64_b32 v78, v50, v49 offset0:6 offset1:7
	ds_write2st64_b32 v78, v48, v47 offset0:8 offset1:9
	ds_write2st64_b32 v78, v46, v45 offset0:10 offset1:11
	ds_write2st64_b32 v78, v44, v43 offset0:12 offset1:13
	ds_write2st64_b32 v78, v42, v41 offset0:14 offset1:15
	ds_write2st64_b32 v78, v40, v39 offset0:16 offset1:17
	ds_write2st64_b32 v78, v38, v37 offset0:18 offset1:19
	ds_write2st64_b32 v78, v36, v33 offset0:20 offset1:21
	ds_write2st64_b32 v78, v32, v31 offset0:22 offset1:23
	ds_write2st64_b32 v78, v30, v29 offset0:24 offset1:25
	ds_write2st64_b32 v78, v28, v27 offset0:26 offset1:27
	ds_write2st64_b32 v78, v26, v25 offset0:28 offset1:29
	ds_write2st64_b32 v78, v24, v23 offset0:30 offset1:31
	ds_write_b32 v78, v22 offset:8192
	s_waitcnt lgkmcnt(0)
	s_barrier
